# v90 + earlyinv2: one buffer_inv per workgroup issued in front of its arrival atomic (overlaps the arrival round trip; leader write-back wait no longer includes it)
# speedup vs baseline: 1.0219x; 1.0046x over previous
.LBB0_746:
	buffer_inv sc1
	s_mov_b64 s[18:19], exec
	v_mbcnt_lo_u32_b32 v3, s18, 0
	v_mbcnt_hi_u32_b32 v3, s19, v3
	v_cmp_eq_u32_e32 vcc, 0, v3
	s_and_saveexec_b64 s[14:15], vcc
	s_cbranch_execz .LBB0_748
	s_bcnt1_i32_b64 s7, s[18:19]
	v_readlane_b32 s8, v255, 4
	v_mov_b32_e32 v5, s7
	v_readlane_b32 s9, v255, 5
	s_nop 4
	global_atomic_add v5, v181, v5, s[8:9] sc0
.LBB0_748:
	s_or_b64 exec, exec, s[14:15]
	v_cvt_f32_u32_e32 v6, v4
	s_waitcnt vmcnt(0)
	v_readfirstlane_b32 s7, v5
	v_sub_u32_e32 v5, 0, v4
	v_rcp_iflag_f32_e32 v6, v6
	v_add_u32_e32 v7, s7, v3
	v_mul_f32_e32 v6, 0x4f7ffffe, v6
	v_cvt_u32_f32_e32 v6, v6
	v_mul_lo_u32 v3, v5, v6
	v_mul_hi_u32 v3, v6, v3
	v_add_u32_e32 v3, v6, v3
	v_mul_hi_u32 v3, v7, v3
	v_mul_lo_u32 v5, v3, v4
	v_sub_u32_e32 v5, v7, v5
	v_add_u32_e32 v6, 1, v3
	v_cmp_ge_u32_e32 vcc, v5, v4
	s_nop 1
	v_cndmask_b32_e32 v3, v3, v6, vcc
	v_sub_u32_e32 v6, v5, v4
	v_cndmask_b32_e32 v5, v5, v6, vcc
	v_add_u32_e32 v6, 1, v3
	v_cmp_ge_u32_e32 vcc, v5, v4
	v_add_u32_e32 v5, 1, v7
	s_nop 0
	v_cndmask_b32_e32 v3, v3, v6, vcc
	v_mul_lo_u32 v6, v4, v3
	v_add_u32_e32 v4, v6, v4
	v_cmp_ne_u32_e32 vcc, v5, v4
	s_and_saveexec_b64 s[8:9], vcc
	s_xor_b64 s[14:15], exec, s[8:9]
	s_cbranch_execz .LBB0_762
	v_readlane_b32 s8, v255, 6
	v_readlane_b32 s9, v255, 7
	s_waitcnt lgkmcnt(0)
	s_nop 3
	global_load_dword v2, v181, s[8:9] offset:2048 sc1
	s_waitcnt vmcnt(0)
	v_cmp_lt_u32_e32 vcc, v2, v4
	s_and_saveexec_b64 s[18:19], vcc
	s_cbranch_execz .LBB0_761
	s_mov_b32 s7, 1
	s_mov_b64 s[22:23], 0
	s_branch .LBB0_752

.LBB0_961:
	buffer_inv sc1
	s_mov_b64 s[18:19], exec
	v_mbcnt_lo_u32_b32 v3, s18, 0
	v_mbcnt_hi_u32_b32 v3, s19, v3
	v_cmp_eq_u32_e32 vcc, 0, v3
	s_and_saveexec_b64 s[14:15], vcc
	s_cbranch_execz .LBB0_963
	s_bcnt1_i32_b64 s6, s[18:19]
	v_mov_b32_e32 v5, s6
	v_readlane_b32 s6, v255, 4
	v_readlane_b32 s7, v255, 5
	s_nop 4
	global_atomic_add v5, v181, v5, s[6:7] sc0
.LBB0_963:
	s_or_b64 exec, exec, s[14:15]
	v_cvt_f32_u32_e32 v6, v4
	s_waitcnt vmcnt(0)
	v_readfirstlane_b32 s6, v5
	v_sub_u32_e32 v5, 0, v4
	v_rcp_iflag_f32_e32 v6, v6
	v_add_u32_e32 v7, s6, v3
	v_mul_f32_e32 v6, 0x4f7ffffe, v6
	v_cvt_u32_f32_e32 v6, v6
	v_mul_lo_u32 v3, v5, v6
	v_mul_hi_u32 v3, v6, v3
	v_add_u32_e32 v3, v6, v3
	v_mul_hi_u32 v3, v7, v3
	v_mul_lo_u32 v5, v3, v4
	v_sub_u32_e32 v5, v7, v5
	v_add_u32_e32 v6, 1, v3
	v_cmp_ge_u32_e32 vcc, v5, v4
	s_nop 1
	v_cndmask_b32_e32 v3, v3, v6, vcc
	v_sub_u32_e32 v6, v5, v4
	v_cndmask_b32_e32 v5, v5, v6, vcc
	v_add_u32_e32 v6, 1, v3
	v_cmp_ge_u32_e32 vcc, v5, v4
	v_add_u32_e32 v5, 1, v7
	s_nop 0
	v_cndmask_b32_e32 v3, v3, v6, vcc
	v_mul_lo_u32 v6, v4, v3
	v_add_u32_e32 v4, v6, v4
	v_cmp_ne_u32_e32 vcc, v5, v4
	s_and_saveexec_b64 s[6:7], vcc
	s_xor_b64 s[14:15], exec, s[6:7]
	s_cbranch_execz .LBB0_977
	v_readlane_b32 s6, v255, 6
	v_readlane_b32 s7, v255, 7
	s_waitcnt lgkmcnt(0)
	s_nop 3
	global_load_dword v2, v181, s[6:7] offset:2048 sc1
	s_waitcnt vmcnt(0)
	v_cmp_lt_u32_e32 vcc, v2, v4
	s_and_saveexec_b64 s[18:19], vcc
	s_cbranch_execz .LBB0_976
	s_mov_b32 s6, 1
	s_mov_b64 s[22:23], 0
	s_branch .LBB0_967

.LBB0_1370:
	buffer_inv sc1
	s_mov_b64 s[22:23], exec
	v_mbcnt_lo_u32_b32 v3, s22, 0
	v_mbcnt_hi_u32_b32 v3, s23, v3
	v_cmp_eq_u32_e32 vcc, 0, v3
	s_and_saveexec_b64 s[18:19], vcc
	s_cbranch_execz .LBB0_1372
	s_bcnt1_i32_b64 s7, s[22:23]
	v_readlane_b32 s8, v255, 4
	v_mov_b32_e32 v5, s7
	v_readlane_b32 s9, v255, 5
	s_nop 4
	global_atomic_add v5, v181, v5, s[8:9] sc0
.LBB0_1372:
	s_or_b64 exec, exec, s[18:19]
	v_cvt_f32_u32_e32 v6, v4
	s_waitcnt vmcnt(0)
	v_readfirstlane_b32 s7, v5
	v_sub_u32_e32 v5, 0, v4
	v_rcp_iflag_f32_e32 v6, v6
	v_add_u32_e32 v7, s7, v3
	v_mul_f32_e32 v6, 0x4f7ffffe, v6
	v_cvt_u32_f32_e32 v6, v6
	v_mul_lo_u32 v3, v5, v6
	v_mul_hi_u32 v3, v6, v3
	v_add_u32_e32 v3, v6, v3
	v_mul_hi_u32 v3, v7, v3
	v_mul_lo_u32 v5, v3, v4
	v_sub_u32_e32 v5, v7, v5
	v_add_u32_e32 v6, 1, v3
	v_cmp_ge_u32_e32 vcc, v5, v4
	s_nop 1
	v_cndmask_b32_e32 v3, v3, v6, vcc
	v_sub_u32_e32 v6, v5, v4
	v_cndmask_b32_e32 v5, v5, v6, vcc
	v_add_u32_e32 v6, 1, v3
	v_cmp_ge_u32_e32 vcc, v5, v4
	v_add_u32_e32 v5, 1, v7
	s_nop 0
	v_cndmask_b32_e32 v3, v3, v6, vcc
	v_mul_lo_u32 v6, v4, v3
	v_add_u32_e32 v4, v6, v4
	v_cmp_ne_u32_e32 vcc, v5, v4
	s_and_saveexec_b64 s[8:9], vcc
	s_xor_b64 s[18:19], exec, s[8:9]
	s_cbranch_execz .LBB0_1386
	v_readlane_b32 s8, v255, 6
	v_readlane_b32 s9, v255, 7
	s_waitcnt lgkmcnt(0)
	s_nop 3
	global_load_dword v2, v181, s[8:9] offset:2048 sc1
	s_waitcnt vmcnt(0)
	v_cmp_lt_u32_e32 vcc, v2, v4
	s_and_saveexec_b64 s[22:23], vcc
	s_cbranch_execz .LBB0_1385
	s_mov_b32 s7, 1
	s_mov_b64 s[24:25], 0
	s_branch .LBB0_1376

.LBB0_1515:
	buffer_inv sc1
	s_mov_b64 s[14:15], exec
	v_mbcnt_lo_u32_b32 v3, s14, 0
	v_mbcnt_hi_u32_b32 v3, s15, v3
	v_cmp_eq_u32_e32 vcc, 0, v3
	s_and_saveexec_b64 s[10:11], vcc
	s_cbranch_execz .LBB0_1517
	s_bcnt1_i32_b64 s6, s[14:15]
	v_mov_b32_e32 v5, s6
	v_readlane_b32 s6, v255, 4
	v_readlane_b32 s7, v255, 5
	s_nop 4
	global_atomic_add v5, v181, v5, s[6:7] sc0
.LBB0_1517:
	s_or_b64 exec, exec, s[10:11]
	v_cvt_f32_u32_e32 v6, v4
	s_waitcnt vmcnt(0)
	v_readfirstlane_b32 s6, v5
	v_sub_u32_e32 v5, 0, v4
	v_rcp_iflag_f32_e32 v6, v6
	v_add_u32_e32 v7, s6, v3
	v_mul_f32_e32 v6, 0x4f7ffffe, v6
	v_cvt_u32_f32_e32 v6, v6
	v_mul_lo_u32 v3, v5, v6
	v_mul_hi_u32 v3, v6, v3
	v_add_u32_e32 v3, v6, v3
	v_mul_hi_u32 v3, v7, v3
	v_mul_lo_u32 v5, v3, v4
	v_sub_u32_e32 v5, v7, v5
	v_add_u32_e32 v6, 1, v3
	v_cmp_ge_u32_e32 vcc, v5, v4
	s_nop 1
	v_cndmask_b32_e32 v3, v3, v6, vcc
	v_sub_u32_e32 v6, v5, v4
	v_cndmask_b32_e32 v5, v5, v6, vcc
	v_add_u32_e32 v6, 1, v3
	v_cmp_ge_u32_e32 vcc, v5, v4
	v_add_u32_e32 v5, 1, v7
	s_nop 0
	v_cndmask_b32_e32 v3, v3, v6, vcc
	v_mul_lo_u32 v6, v4, v3
	v_add_u32_e32 v4, v6, v4
	v_cmp_ne_u32_e32 vcc, v5, v4
	s_and_saveexec_b64 s[6:7], vcc
	s_xor_b64 s[10:11], exec, s[6:7]
	s_cbranch_execz .LBB0_1531
	v_readlane_b32 s6, v255, 6
	v_readlane_b32 s7, v255, 7
	s_waitcnt lgkmcnt(0)
	s_nop 3
	global_load_dword v2, v181, s[6:7] offset:2048 sc1
	s_waitcnt vmcnt(0)
	v_cmp_lt_u32_e32 vcc, v2, v4
	s_and_saveexec_b64 s[14:15], vcc
	s_cbranch_execz .LBB0_1530
	s_mov_b32 s6, 1
	s_mov_b64 s[18:19], 0
	s_branch .LBB0_1521
